# redundant grid barrier between P8 and the now-empty P9 removed (one barrier remains between P8 and P10)
# speedup vs baseline: 1.0358x; 1.0027x over previous
; DI unsigned xb_ld(unsigned* p)              { return __hip_atomic_load(p, __ATOMIC_RELAXED, __HIP_MEMORY_SCOPE_AGENT); }
; DI unsigned xb_add(unsigned* p, unsigned v) { return __hip_atomic_fetch_add(p, v, __ATOMIC_RELAXED, __HIP_MEMORY_SCOPE_AGENT); }
; #define XB_SPIN(cond, bar) do { unsigned _sp = 0; while (cond) { __builtin_amdgcn_s_sleep(1); \
;     if ((++_sp & 255u) == 0u) { if (xb_ld(&(bar)[XB_TMO])) break; if (_sp > XB_SPIN_CAP) { atomicAdd(&(bar)[XB_TMO], 1u); break; } } } } while (0)
; DI void xcd_barrier(const XcdBarrier& b) {
;     asm volatile("s_waitcnt vmcnt(0)" ::: "memory");
;     __syncthreads();
;     if (threadIdx.x == 0) {
;         unsigned* bar = b.bar;
;         __builtin_amdgcn_s_waitcnt(0);
;         unsigned nloc = b.st[0], nx = b.st[1];
;         if (nloc == 0u) { xcd_barrier_complete(bar, b.x, nloc, nx); b.st[0] = nloc; b.st[1] = nx; }
;         const unsigned old = xb_add(&bar[XB_XSUB(b.x)], 1u);
;         const unsigned gen = old / nloc;
;         if (old + 1u == (gen + 1u) * nloc) {
;             __builtin_amdgcn_fence(__ATOMIC_RELEASE, "agent");
;             asm volatile("s_waitcnt vmcnt(0)" ::: "memory");
;             const unsigned og = xb_add(&bar[XB_TOP], 1u);
;             const unsigned tg = og / nx;
;             if (og + 1u == (tg + 1u) * nx) xb_add(&bar[XB_TOPGEN], 1u);
;             else XB_SPIN(xb_ld(&bar[XB_TOPGEN]) == tg, bar);
;             __builtin_amdgcn_fence(__ATOMIC_ACQUIRE, "agent");
;             xb_add(&bar[XB_XGEN(b.x)], 1u);
;             asm volatile("s_waitcnt vmcnt(0)" ::: "memory");
;         } else {
;             XB_SPIN(xb_ld(&bar[XB_XGEN(b.x)]) == gen, bar);
;             __builtin_amdgcn_fence(__ATOMIC_ACQUIRE, "agent");
;             asm volatile("s_waitcnt vmcnt(0)" ::: "memory");
;         }
;     }
;     __syncthreads();
; }
; __global__ void __launch_bounds__(512, 1) k_mega(Params P) {
;     ...
;   phase9(P, smem); xcd_barrier(xb);
.LBB0_1071:
	s_branch .LBB0_1126
	s_waitcnt vmcnt(0)
	s_barrier
	s_mov_b64 s[0:1], exec
	v_readlane_b32 s4, v254, 10
	v_readlane_b32 s5, v254, 11
	s_and_b64 s[4:5], s[0:1], s[4:5]
	s_mov_b64 exec, s[4:5]
	s_cbranch_execz .LBB0_1123
	s_add_i32 s2, 0, 0x22a00
	v_mov_b32_e32 v0, s2
	s_waitcnt vmcnt(0) expcnt(0) lgkmcnt(0)
	ds_read_b32 v2, v0
	s_add_i32 s2, 0, 0x22a04
	v_mov_b32_e32 v0, s2
	ds_read_b32 v0, v0
	s_waitcnt lgkmcnt(1)
	v_cmp_ne_u32_e32 vcc, 0, v2
	s_cbranch_vccnz .LBB0_1087
	s_add_u32 s6, s78, 0x18e00200
	s_addc_u32 s7, s79, 0
	s_add_u32 s10, s78, 0x18e00400
	s_addc_u32 s11, s79, 0
	s_add_u32 s12, s78, 0x18e00500
	s_addc_u32 s13, s79, 0
	s_add_u32 s14, s78, 0x18e00600
	s_addc_u32 s15, s79, 0
	s_add_u32 s16, s78, 0x18e00700
	s_addc_u32 s17, s79, 0
	s_add_u32 s18, s78, 0x18e00800
	s_addc_u32 s19, s79, 0
	s_add_u32 s20, s78, 0x18e00900
	s_addc_u32 s21, s79, 0
	s_add_u32 s24, s78, 0x18e00a00
	s_addc_u32 s25, s79, 0
	s_add_u32 s26, s78, 0x18e00b00
	s_addc_u32 s27, s79, 0
	s_add_u32 s28, s78, 0x18e00c00
	s_addc_u32 s29, s79, 0
	s_add_u32 s30, s78, 0x18e00d00
	s_addc_u32 s31, s79, 0
	s_add_u32 s34, s78, 0x18e00e00
	s_addc_u32 s35, s79, 0
	s_add_u32 s42, s78, 0x18e00f00
	s_addc_u32 s43, s79, 0
	s_add_u32 s44, s78, 0x18e01000
	s_addc_u32 s45, s79, 0
	s_add_u32 s46, s78, 0x18e01100
	s_addc_u32 s47, s79, 0
	v_readlane_b32 s4, v254, 8
	s_add_u32 s48, s78, 0x18e01200
	v_readlane_b32 s5, v254, 9
	s_addc_u32 s49, s79, 0
	s_mul_i32 s2, s5, s97
	s_add_u32 s8, s78, 0x18e01300
	s_mul_i32 s2, s2, s4
	s_addc_u32 s9, s79, 0
	s_mov_b32 s4, 1
	v_mov_b32_e32 v16, 0
	s_branch .LBB0_1075
